# P3 delta items: item-top wait counts only the conv-row loads (vmcnt(2)), no longer the previous item's two stores
# baseline (speedup 1.0000x reference)
.LBB0_313:
	v_add_u32_e32 v230, 0, v146
	v_add_u32_e32 v34, s49, v146
	ds_write_b128 v230, v[234:237] offset:54272
	ds_write_b128 v209, v[234:237] offset:54272
	ds_write_b128 v210, v[234:237] offset:54272
	s_and_saveexec_b64 s[2:3], s[42:43]
	ds_write_b128 v34, v[30:33] offset:6144
	s_or_b64 exec, exec, s[2:3]
	s_and_saveexec_b64 s[2:3], s[44:45]
	ds_write_b128 v34, v[30:33] offset:14336
	s_or_b64 exec, exec, s[2:3]
	s_and_b32 s68, s53, 7
	s_lshl_b32 s69, s68, 7
	v_and_b32_e32 v88, 31, v0
	v_lshlrev_b32_e32 v88, 4, v88
	v_add_u32_e32 v88, 0x26a00, v88
	ds_read_b128 v[34:37], v88
	ds_read_b128 v[38:41], v88 offset:512
	ds_read_b128 v[50:53], v88 offset:1024
	ds_read_b128 v[54:57], v88 offset:1536
	ds_read_b128 v[58:61], v88 offset:2048
	ds_read_b128 v[42:45], v88 offset:2560
	ds_read_b128 v[46:49], v88 offset:3072
	ds_read_b128 v[62:65], v88 offset:3584
	s_waitcnt vmcnt(2)
	v_lshlrev_b32_e32 v122, 16, v2
	v_and_b32_e32 v123, 0xffff0000, v2
	v_lshlrev_b32_e32 v66, 16, v6
	v_and_b32_e32 v68, 0xffff0000, v6
	v_mov_b32_e32 v67, v122
	v_mov_b32_e32 v69, v123
	v_lshlrev_b32_e32 v96, 16, v10
	v_and_b32_e32 v97, 0xffff0000, v10
	v_lshlrev_b32_e32 v104, 16, v14
	v_and_b32_e32 v105, 0xffff0000, v14
	v_mov_b32_e32 v124, v104
	v_mov_b32_e32 v125, v96
	v_mov_b32_e32 v126, v105
	v_mov_b32_e32 v127, v97
	v_lshlrev_b32_e32 v88, 16, v9
	v_lshlrev_b32_e32 v108, 16, v7
	v_and_b32_e32 v120, 0xffff0000, v7
	v_lshlrev_b32_e32 v109, 16, v3
	v_and_b32_e32 v121, 0xffff0000, v3
	v_lshlrev_b32_e32 v98, 16, v11
	v_and_b32_e32 v99, 0xffff0000, v11
	v_and_b32_e32 v107, 0xffff0000, v15
	v_lshlrev_b32_e32 v106, 16, v15
	v_lshlrev_b32_e32 v100, 16, v12
	v_lshlrev_b32_e32 v114, 16, v16
	v_mov_b32_e32 v128, v106
	v_mov_b32_e32 v129, v98
	v_mov_b32_e32 v130, v107
	v_mov_b32_e32 v131, v99
	v_and_b32_e32 v101, 0xffff0000, v12
	v_and_b32_e32 v115, 0xffff0000, v16
	v_lshlrev_b32_e32 v102, 16, v8
	v_and_b32_e32 v118, 0xffff0000, v8
	v_and_b32_e32 v110, 0xffff0000, v9
	v_and_b32_e32 v111, 0xffff0000, v5
	s_and_b32 s71, s41, 0xffffffc0
	s_waitcnt lgkmcnt(7)
	v_mul_f32_e32 v133, v36, v88
	s_waitcnt lgkmcnt(6)
	v_mov_b32_e32 v134, v38
	v_mov_b32_e32 v136, v39
	v_mov_b32_e32 v138, v40
	s_waitcnt lgkmcnt(5)
	v_mov_b32_e32 v135, v50
	v_mov_b32_e32 v137, v51
	v_pk_mul_f32 v[66:67], v[134:135], v[66:67]
	v_pk_mul_f32 v[68:69], v[136:137], v[68:69]
	v_mov_b32_e32 v248, v66
	v_mov_b32_e32 v249, v68
	v_pk_add_f32 v[248:249], v[248:249], 0 op_sel_hi:[1,0]
	v_mov_b32_e32 v68, v67
	s_waitcnt lgkmcnt(4)
	v_mov_b32_e32 v142, v54
	v_mov_b32_e32 v232, v55
	v_pk_add_f32 v[66:67], v[248:249], v[68:69]
	s_waitcnt lgkmcnt(3)
	v_mov_b32_e32 v143, v58
	v_mov_b32_e32 v233, v59
	v_pk_mul_f32 v[142:143], v[142:143], v[124:125]
	v_pk_mul_f32 v[232:233], v[232:233], v[126:127]
	v_mov_b32_e32 v68, v142
	v_mov_b32_e32 v69, v232
	v_pk_add_f32 v[66:67], v[66:67], v[68:69]
	v_mov_b32_e32 v232, v143
	v_pk_add_f32 v[66:67], v[66:67], v[232:233]
	v_mov_b32_e32 v140, v41
	v_mul_f32_e32 v68, 0xbfb8aa3b, v66
	v_exp_f32_e32 v68, v68
	v_mul_f32_e32 v69, 0xbfb8aa3b, v67
	v_exp_f32_e32 v88, v69
	v_mov_b32_e32 v139, v52
	v_add_f32_e32 v68, 1.0, v68
	v_rcp_f32_e32 v142, v68
	v_add_f32_e32 v68, 1.0, v88
	v_rcp_f32_e32 v143, v68
	v_mov_b32_e32 v141, v53
	v_pk_mul_f32 v[138:139], v[138:139], v[108:109]
	v_pk_mul_f32 v[140:141], v[140:141], v[120:121]
	v_mov_b32_e32 v134, v56
	v_mov_b32_e32 v136, v57
	v_mov_b32_e32 v135, v60
	v_mov_b32_e32 v137, v61
	v_pk_mul_f32 v[66:67], v[66:67], v[142:143]
	v_mov_b32_e32 v142, v140
	v_mov_b32_e32 v143, v138
	s_waitcnt lgkmcnt(2)
	v_mov_b32_e32 v238, v42
	v_pk_mul_f32 v[128:129], v[134:135], v[128:129]
	v_pk_mul_f32 v[130:131], v[136:137], v[130:131]
	s_waitcnt lgkmcnt(1)
	v_mov_b32_e32 v239, v46
	v_mov_b32_e32 v124, v114
	v_mov_b32_e32 v125, v100
	v_pk_add_f32 v[142:143], v[142:143], 0 op_sel_hi:[1,0]
	v_mov_b32_e32 v138, v141
	v_pk_mul_f32 v[134:135], v[238:239], v[124:125]
	v_mov_b32_e32 v124, v43
	v_mov_b32_e32 v125, v47
	v_mov_b32_e32 v126, v115
	v_mov_b32_e32 v127, v101
	v_pk_add_f32 v[138:139], v[142:143], v[138:139]
	v_mov_b32_e32 v140, v130
	v_mov_b32_e32 v141, v128
	v_pk_mul_f32 v[136:137], v[124:125], v[126:127]
	v_lshlrev_b32_e32 v124, 16, v4
	v_pk_add_f32 v[138:139], v[138:139], v[140:141]
	v_mov_b32_e32 v128, v131
	v_and_b32_e32 v125, 0xffff0000, v4
	v_mov_b32_e32 v126, v34
	s_waitcnt lgkmcnt(0)
	v_mov_b32_e32 v127, v62
	v_mov_b32_e32 v103, v124
	v_pk_add_f32 v[128:129], v[138:139], v[128:129]
	v_pk_mul_f32 v[238:239], v[126:127], v[102:103]
	v_mov_b32_e32 v102, v35
	v_mov_b32_e32 v103, v63
	v_mov_b32_e32 v119, v125
	v_mul_f32_e32 v68, 0xbfb8aa3b, v129
	v_pk_mul_f32 v[240:241], v[102:103], v[118:119]
	v_exp_f32_e32 v68, v68
	v_mul_f32_e32 v88, 0xbfb8aa3b, v128
	v_exp_f32_e32 v88, v88
	v_mov_b32_e32 v140, v240
	v_mov_b32_e32 v141, v238
	v_pk_add_f32 v[140:141], v[140:141], 0 op_sel_hi:[1,0]
	v_mov_b32_e32 v238, v241
	v_pk_add_f32 v[140:141], v[140:141], v[238:239]
	v_mov_b32_e32 v142, v136
	v_mov_b32_e32 v143, v134
	v_add_f32_e32 v68, 1.0, v68
	v_pk_add_f32 v[140:141], v[140:141], v[142:143]
	v_mov_b32_e32 v134, v137
	v_rcp_f32_e32 v139, v68
	v_add_f32_e32 v68, 1.0, v88
	v_pk_add_f32 v[134:135], v[140:141], v[134:135]
	v_rcp_f32_e32 v138, v68
	v_mul_f32_e32 v68, 0xbfb8aa3b, v135
	v_exp_f32_e32 v68, v68
	v_and_b32_e32 v103, 0xffff0000, v13
	v_and_b32_e32 v119, 0xffff0000, v17
	v_mov_b32_e32 v232, v37
	v_mov_b32_e32 v233, v65
	v_mov_b32_e32 v126, v45
	v_mov_b32_e32 v127, v49
	v_mov_b32_e32 v246, v119
	v_mov_b32_e32 v247, v103
	v_pk_mul_f32 v[232:233], v[232:233], v[110:111]
	v_pk_mul_f32 v[246:247], v[126:127], v[246:247]
	v_lshlrev_b32_e32 v126, 16, v5
	v_add_f32_e32 v68, 1.0, v68
	v_mov_b32_e32 v132, v232
	v_lshlrev_b32_e32 v118, 16, v17
	v_mul_f32_e32 v69, v64, v126
	v_rcp_f32_e32 v137, v68
	v_pk_add_f32 v[132:133], v[132:133], 0 op_sel_hi:[1,0]
	v_mov_b32_e32 v68, v233
	v_lshlrev_b32_e32 v102, 16, v13
	v_mul_f32_e32 v245, v44, v118
	v_pk_add_f32 v[68:69], v[132:133], v[68:69]
	v_mov_b32_e32 v244, v246
	v_mul_f32_e32 v243, v48, v102
	v_pk_add_f32 v[68:69], v[68:69], v[244:245]
	v_mov_b32_e32 v242, v247
	v_mul_f32_e32 v88, 0xbfb8aa3b, v134
	v_pk_add_f32 v[68:69], v[68:69], v[242:243]
	v_exp_f32_e32 v88, v88
	v_mul_f32_e32 v91, 0xbfb8aa3b, v69
	v_exp_f32_e32 v91, v91
	v_mul_f32_e32 v95, 0xbfb8aa3b, v68
	v_exp_f32_e32 v95, v95
	v_add_f32_e32 v88, 1.0, v88
	v_rcp_f32_e32 v136, v88
	v_add_f32_e32 v88, 1.0, v91
	v_rcp_f32_e32 v133, v88
	v_add_f32_e32 v88, 1.0, v95
	v_pk_mul_f32 v[130:131], v[66:67], v[66:67]
	v_pk_mul_f32 v[128:129], v[128:129], v[138:139]
	v_rcp_f32_e32 v132, v88
	v_pk_mul_f32 v[138:139], v[128:129], v[128:129]
	v_add_f32_e32 v88, v130, v131
	v_pk_mul_f32 v[134:135], v[134:135], v[136:137]
	v_add_f32_e32 v88, v139, v88
	v_pk_mul_f32 v[136:137], v[134:135], v[134:135]
	v_add_f32_e32 v88, v138, v88
	v_pk_mul_f32 v[68:69], v[68:69], v[132:133]
	v_add_f32_e32 v88, v137, v88
	v_pk_mul_f32 v[132:133], v[68:69], v[68:69]
	v_add_f32_e32 v88, v136, v88
	v_add_f32_e32 v88, v133, v88
	v_add_f32_e32 v88, v132, v88
	s_nop 1
	v_add_f32_dpp v88, v88, v88 quad_perm:[1,0,3,2] row_mask:0xf bank_mask:0xf
	s_nop 1
	v_add_f32_dpp v88, v88, v88 quad_perm:[2,3,0,1] row_mask:0xf bank_mask:0xf
	s_nop 1
	v_add_f32_dpp v88, v88, v88 row_ror:4 row_mask:0xf bank_mask:0xf
	s_nop 1
	v_add_f32_dpp v88, v88, v88 row_ror:8 row_mask:0xf bank_mask:0xf
	v_add_f32_e32 v88, 0x358637bd, v88
	v_mul_f32_e32 v91, 0x4b800000, v88
	v_cmp_gt_f32_e32 vcc, s52, v88
	s_nop 1
	v_cndmask_b32_e32 v88, v88, v91, vcc
	v_rsq_f32_e32 v88, v88
	s_nop 0
	v_mul_f32_e32 v91, 0x45800000, v88
	v_cndmask_b32_e32 v88, v88, v91, vcc
	v_mul_f32_e32 v88, v179, v88
	v_mul_f32_e32 v116, v66, v88
	v_mul_f32_e32 v232, v67, v88
	v_mul_f32_e32 v112, v129, v88
	v_mul_f32_e32 v231, v128, v88
	v_mul_f32_e32 v110, v135, v88
	v_mul_f32_e32 v95, v134, v88
	v_mul_f32_e32 v108, v69, v88
	v_mul_f32_e32 v91, v68, v88
	v_cvt_pk_bf16_f32 v66, v116, v232
	v_cvt_pk_bf16_f32 v67, v112, v231
	v_cvt_pk_bf16_f32 v68, v110, v95
	v_cvt_pk_bf16_f32 v69, v108, v91
	v_lshlrev_b32_e32 v88, 1, v86
	ds_write_b128 v224, v[66:69]
	s_and_saveexec_b64 s[2:3], s[38:39]
	s_cbranch_execz .LBB0_319
	v_add_u32_e32 v128, s71, v180
	v_ashrrev_i32_e32 v129, 31, v128
	v_lshlrev_b64 v[128:129], 11, v[128:129]
	v_lshl_add_u64 v[128:129], s[72:73], 0, v[128:129]
	s_lshl_b32 s80, s69, 1
	v_lshl_add_u64 v[128:129], v[128:129], 0, s[80:81]
	v_lshl_add_u64 v[128:129], v[128:129], 0, v[88:89]
	global_store_dwordx4 v[128:129], v[66:69], off
